# DSA attention: the four query-fragment loads of a query issued together (one drain instead of four serialized load+drain pairs)
# speedup vs baseline: 1.0016x; 1.0012x over previous
; DI f32x4 mfma16(bf16x8 a, bf16x8 b, f32x4 c) { return __builtin_amdgcn_mfma_f32_16x16x32_bf16(a, b, c, 0, 0, 0); }
; DI void dsa_task(const Params& p, int l, int isP, int b, int tq, char* smem, const bool dry) {
;     ...
; #pragma unroll
;       for (int j = 0; j < 2; j++) {
;         const bf16_t* qp = p.qa + (size_t)tok * 512 + (j * 4 + (cl & 3)) * 64 + g4 * 8;
;         const bf16x8 bq0 = *(const bf16x8*)qp;
;         const bf16x8 bq1 = *(const bf16x8*)(qp + 32);
;         f32x4 lg[4];
; #pragma unroll
;         for (int tt = 0; tt < 4; tt++) {
;           f32x4 a = (f32x4){0.f, 0.f, 0.f, 0.f};
;           a = mfma16(kf[j][tt][0], bq0, a);
;           a = mfma16(kf[j][tt][1], bq1, a);
;           lg[tt] = a;
;         }
;         float m = -1e30f;
; #pragma unroll
;         for (int tt = 0; tt < 4; tt++)
; #pragma unroll
;           for (int r = 0; r < 4; r++) m = fmaxf(m, lg[tt][r]);
;         m = red4_max(m);
;         float sum = 0.f;
; #pragma unroll
;         for (int tt = 0; tt < 4; tt++)
; #pragma unroll
;           for (int r = 0; r < 4; r++) {
;             const float e = __expf(lg[tt][r] - m);
;             lg[tt][r] = e;
;             sum += e;
;           }
;         sum = red4_sum(sum);
.LBB0_1656:
	s_or_saveexec_b64 s[14:15], s[14:15]
	v_mov_b64_e32 v[132:133], s[16:17]
	s_xor_b64 exec, exec, s[14:15]
	s_cbranch_execz .LBB0_1651
	s_load_dwordx2 s[18:19], s[72:73], 0x0
	s_lshl_b64 s[16:17], s[44:45], 10
	v_lshlrev_b32_e32 v132, 1, v174
	v_mov_b32_e32 v133, v164
	s_waitcnt lgkmcnt(0)
	s_add_u32 s18, s18, s16
	s_addc_u32 s19, s19, s17
	v_lshl_add_u64 v[134:135], v[172:173], 1, s[18:19]
	v_lshl_add_u64 v[132:133], v[134:135], 0, v[132:133]
	global_load_dwordx4 v[134:137], v[132:133], off
	global_load_dwordx4 v[224:227], v[132:133], off offset:64
	global_load_dwordx4 v[228:231], v[132:133], off offset:512
	global_load_dwordx4 v[232:235], v[132:133], off offset:576
	s_waitcnt vmcnt(0)
	v_mfma_f32_16x16x32_bf16 v[108:111], v[108:111], v[134:137], 0
	v_mfma_f32_16x16x32_bf16 v[112:115], v[112:115], v[134:137], 0
	v_mfma_f32_16x16x32_bf16 v[120:123], v[120:123], v[134:137], 0
	v_mfma_f32_16x16x32_bf16 v[128:131], v[128:131], v[134:137], 0
	v_mfma_f32_16x16x32_bf16 v[108:111], v[100:103], v[224:227], v[108:111]
	s_nop 7
	v_max3_f32 v100, v108, s77, v109
	v_mfma_f32_16x16x32_bf16 v[102:105], v[104:107], v[224:227], v[112:115]
	v_max3_f32 v100, v100, v110, v111
	v_mfma_f32_16x16x32_bf16 v[112:115], v[116:119], v[224:227], v[120:123]
	v_mfma_f32_16x16x32_bf16 v[116:119], v[124:127], v[224:227], v[128:131]
	s_nop 4
	v_max3_f32 v100, v100, v102, v103
	v_max3_f32 v100, v100, v104, v105
	v_max3_f32 v100, v100, v112, v113
	v_max3_f32 v100, v100, v114, v115
	v_max3_f32 v100, v100, v116, v117
	v_max3_f32 v100, v100, v118, v119
	v_mov_b32_e32 v101, v100
	s_nop 1
	v_permlane16_swap_b32_e32 v100, v101
	v_max_f32_e32 v101, v101, v101
	v_max_f32_e32 v100, v100, v100
	v_max_f32_e32 v100, v100, v101
	v_mov_b32_e32 v101, v100
	s_nop 1
	v_permlane32_swap_b32_e32 v100, v101
	v_max_f32_e32 v101, v101, v101
	v_max_f32_e32 v100, v100, v100
	v_max_f32_e32 v100, v100, v101
	v_sub_f32_e32 v101, v108, v100
	v_sub_f32_e32 v106, v109, v100
	v_sub_f32_e32 v102, v102, v100
	v_mul_f32_e32 v101, 0x3fb8aa3b, v101
	v_sub_f32_e32 v107, v110, v100
	v_sub_f32_e32 v108, v111, v100
	v_sub_f32_e32 v103, v103, v100
	v_sub_f32_e32 v111, v114, v100
	v_sub_f32_e32 v114, v117, v100
	v_mul_f32_e32 v106, 0x3fb8aa3b, v106
	v_mul_f32_e32 v117, 0x3fb8aa3b, v102
	v_exp_f32_e32 v102, v101
	v_sub_f32_e32 v104, v104, v100
	v_sub_f32_e32 v109, v112, v100
	v_sub_f32_e32 v112, v115, v100
	v_sub_f32_e32 v115, v118, v100
	v_mul_f32_e32 v107, 0x3fb8aa3b, v107
	v_mul_f32_e32 v118, 0x3fb8aa3b, v103
	v_exp_f32_e32 v103, v106
	v_sub_f32_e32 v105, v105, v100
	v_sub_f32_e32 v110, v113, v100
	v_sub_f32_e32 v113, v116, v100
	v_sub_f32_e32 v116, v119, v100
	v_mul_f32_e32 v108, 0x3fb8aa3b, v108
	v_mul_f32_e32 v119, 0x3fb8aa3b, v104
	v_exp_f32_e32 v104, v107
	v_mul_f32_e32 v120, 0x3fb8aa3b, v105
	v_exp_f32_e32 v105, v108
	v_exp_f32_e32 v106, v117
	v_add_f32_e32 v101, 0, v102
	v_exp_f32_e32 v107, v118
	v_add_f32_e32 v101, v103, v101
	v_exp_f32_e32 v108, v119
	v_add_f32_e32 v101, v104, v101
	v_mul_f32_e32 v121, 0x3fb8aa3b, v109
	v_exp_f32_e32 v109, v120
	v_add_f32_e32 v101, v105, v101
	v_mul_f32_e32 v122, 0x3fb8aa3b, v110
	v_exp_f32_e32 v110, v121
	v_add_f32_e32 v101, v106, v101
	v_mul_f32_e32 v123, 0x3fb8aa3b, v111
	v_exp_f32_e32 v111, v122
	v_add_f32_e32 v101, v107, v101
	v_mul_f32_e32 v124, 0x3fb8aa3b, v112
	v_exp_f32_e32 v112, v123
	v_add_f32_e32 v101, v108, v101
	v_mul_f32_e32 v125, 0x3fb8aa3b, v113
	v_exp_f32_e32 v113, v124
	v_add_f32_e32 v101, v109, v101
	v_mul_f32_e32 v126, 0x3fb8aa3b, v114
	v_exp_f32_e32 v114, v125
	v_add_f32_e32 v101, v110, v101
	v_mul_f32_e32 v127, 0x3fb8aa3b, v115
	v_exp_f32_e32 v115, v126
	v_add_f32_e32 v101, v111, v101
	v_mul_f32_e32 v128, 0x3fb8aa3b, v116
	v_exp_f32_e32 v116, v127
	v_add_f32_e32 v101, v112, v101
	v_exp_f32_e32 v117, v128
	v_add_f32_e32 v101, v113, v101
	v_add_f32_e32 v101, v114, v101
	v_add_f32_e32 v101, v115, v101
	v_add_f32_e32 v101, v116, v101
	v_add_f32_e32 v101, v117, v101
	v_mov_b32_e32 v118, v101
	s_nop 1
	v_permlane16_swap_b32_e32 v101, v118
	v_add_f32_e32 v101, v101, v118
	v_mov_b32_e32 v118, v101
	s_nop 1
	v_permlane32_swap_b32_e32 v101, v118
	s_and_saveexec_b64 s[18:19], s[12:13]
	v_add_f32_e32 v101, v101, v118
	v_add_u32_e32 v118, s22, v217
	ds_write_b64 v118, v[100:101] offset:61952
	s_or_b64 exec, exec, s[18:19]
	v_mfma_f32_16x16x32_bf16 v[76:79], v[76:79], v[228:231], 0
	v_mfma_f32_16x16x32_bf16 v[80:83], v[80:83], v[228:231], 0
	v_mfma_f32_16x16x32_bf16 v[88:91], v[88:91], v[228:231], 0
	v_mfma_f32_16x16x32_bf16 v[96:99], v[96:99], v[228:231], 0
	v_mfma_f32_16x16x32_bf16 v[76:79], v[68:71], v[232:235], v[76:79]
	s_nop 7
	v_max3_f32 v68, v76, s77, v77
	v_mfma_f32_16x16x32_bf16 v[70:73], v[72:75], v[232:235], v[80:83]
	v_max3_f32 v68, v68, v78, v79
	v_mfma_f32_16x16x32_bf16 v[80:83], v[84:87], v[232:235], v[88:91]
	v_mfma_f32_16x16x32_bf16 v[84:87], v[92:95], v[232:235], v[96:99]
	s_nop 4
	v_max3_f32 v68, v68, v70, v71
	v_max3_f32 v68, v68, v72, v73
	v_max3_f32 v68, v68, v80, v81
	v_max3_f32 v68, v68, v82, v83
	v_max3_f32 v68, v68, v84, v85
	v_max3_f32 v68, v68, v86, v87
	v_mov_b32_e32 v69, v68
	s_nop 1
	v_permlane16_swap_b32_e32 v68, v69
	v_max_f32_e32 v69, v69, v69
	v_max_f32_e32 v68, v68, v68
	v_max_f32_e32 v68, v68, v69
	v_mov_b32_e32 v69, v68
	s_nop 1
	v_permlane32_swap_b32_e32 v68, v69
	v_max_f32_e32 v69, v69, v69
	v_max_f32_e32 v68, v68, v68
	v_max_f32_e32 v68, v68, v69
	v_sub_f32_e32 v69, v76, v68
	v_sub_f32_e32 v74, v77, v68
	v_sub_f32_e32 v70, v70, v68
	v_mul_f32_e32 v69, 0x3fb8aa3b, v69
	v_sub_f32_e32 v75, v78, v68
	v_sub_f32_e32 v76, v79, v68
	v_sub_f32_e32 v71, v71, v68
	v_sub_f32_e32 v79, v82, v68
	v_sub_f32_e32 v82, v85, v68
; DI void dsa_task(const Params& p, int l, int isP, int b, int tq, char* smem, const bool dry) {
;     ...
;         float sum = 0.f;
; #pragma unroll
;         for (int tt = 0; tt < 4; tt++)
; #pragma unroll
;           for (int r = 0; r < 4; r++) {
;             const float e = __expf(lg[tt][r] - m);
;             lg[tt][r] = e;
;             sum += e;
;           }
;         sum = red4_sum(sum);
; #pragma unroll
;         for (int sI = 0; sI < 2; sI++) {
;           pb[j][sI].u[0] = pack2(lg[2 * sI][0], lg[2 * sI][1]);
;           pb[j][sI].u[1] = pack2(lg[2 * sI][2], lg[2 * sI][3]);
;           pb[j][sI].u[2] = pack2(lg[2 * sI + 1][0], lg[2 * sI + 1][1]);
;           pb[j][sI].u[3] = pack2(lg[2 * sI + 1][2], lg[2 * sI + 1][3]);
;         }
;         if (cl < 4 && g4 == 0) {
;           mlb[(wave * 8 + j * 4 + cl) * 2] = m;
;           mlb[(wave * 8 + j * 4 + cl) * 2 + 1] = sum;
;         }
;       }
; #pragma unroll
;       for (int tt = 0; tt < 4; tt++) {
;         const int pos = idxl[qn * 256 + wave * 64 + tt * 16 + cl];
; #pragma unroll
;         for (int j = 0; j < 2; j++) {
;           const bf16_t* kr = Ks + (size_t)pos * 128 + j * 64 + g4 * 8;
;           kf[j][tt][0] = *(const bf16x8*)kr;
;           kf[j][tt][1] = *(const bf16x8*)(kr + 32);
;         }
;       }
;       f32x4 o[2][4];
; #pragma unroll
;       for (int j = 0; j < 2; j++)
; #pragma unroll
;         for (int dt = 0; dt < 4; dt++) o[j][dt] = (f32x4){0.f, 0.f, 0.f, 0.f};
;       const lds_cptr vb = (lds_cptr)(vst + (g4 * 4 + (cl >> 2)) * 288 + (cl & 3) * 8);
;       {
;         *(uint4*)(vst + (0 + g4) * 288 + cl * 16) = vq0;
;         *(uint4*)(vst + (4 + g4) * 288 + cl * 16) = vq1;
;         *(uint4*)(vst + (8 + g4) * 288 + cl * 16) = vq2;
;         *(uint4*)(vst + (12 + g4) * 288 + cl * 16) = vq3;
;         *(uint4*)(vst + (16 + g4) * 288 + cl * 16) = vq4;
;         *(uint4*)(vst + (20 + g4) * 288 + cl * 16) = vq5;
;         *(uint4*)(vst + (24 + g4) * 288 + cl * 16) = vq6;
;         *(uint4*)(vst + (28 + g4) * 288 + cl * 16) = vq7;
;         __builtin_amdgcn_wave_barrier();
; #pragma unroll
;         for (int j = 0; j < 2; j++)
; #pragma unroll
;           for (int dt = 0; dt < 4; dt++) {
;             const s16x4 alo = vtr(vb + (j * 64 + dt * 16) * 2);
;             const s16x4 ahi = vtr(vb + (j * 64 + dt * 16) * 2 + 16 * 288);
	v_mul_f32_e32 v74, 0x3fb8aa3b, v74
	v_mul_f32_e32 v85, 0x3fb8aa3b, v70
	v_exp_f32_e32 v70, v69
	v_sub_f32_e32 v72, v72, v68
	v_sub_f32_e32 v77, v80, v68
	v_sub_f32_e32 v80, v83, v68
	v_sub_f32_e32 v83, v86, v68
	v_mul_f32_e32 v75, 0x3fb8aa3b, v75
	v_mul_f32_e32 v86, 0x3fb8aa3b, v71
	v_exp_f32_e32 v71, v74
	v_sub_f32_e32 v73, v73, v68
	v_sub_f32_e32 v78, v81, v68
	v_sub_f32_e32 v81, v84, v68
	v_sub_f32_e32 v84, v87, v68
	v_mul_f32_e32 v76, 0x3fb8aa3b, v76
	v_mul_f32_e32 v87, 0x3fb8aa3b, v72
	v_exp_f32_e32 v72, v75
	v_mul_f32_e32 v88, 0x3fb8aa3b, v73
	v_exp_f32_e32 v73, v76
	v_exp_f32_e32 v74, v85
	v_add_f32_e32 v69, 0, v70
	v_exp_f32_e32 v75, v86
	v_add_f32_e32 v69, v71, v69
	v_exp_f32_e32 v76, v87
	v_add_f32_e32 v69, v72, v69
	v_mul_f32_e32 v89, 0x3fb8aa3b, v77
	v_exp_f32_e32 v77, v88
	v_add_f32_e32 v69, v73, v69
	v_mul_f32_e32 v90, 0x3fb8aa3b, v78
	v_exp_f32_e32 v78, v89
	v_add_f32_e32 v69, v74, v69
	v_mul_f32_e32 v91, 0x3fb8aa3b, v79
	v_exp_f32_e32 v79, v90
	v_add_f32_e32 v69, v75, v69
	v_mul_f32_e32 v92, 0x3fb8aa3b, v80
	v_exp_f32_e32 v80, v91
	v_add_f32_e32 v69, v76, v69
	v_mul_f32_e32 v93, 0x3fb8aa3b, v81
	v_exp_f32_e32 v81, v92
	v_add_f32_e32 v69, v77, v69
	v_mul_f32_e32 v94, 0x3fb8aa3b, v82
	v_exp_f32_e32 v82, v93
	v_add_f32_e32 v69, v78, v69
	v_mul_f32_e32 v95, 0x3fb8aa3b, v83
	v_exp_f32_e32 v83, v94
	v_add_f32_e32 v69, v79, v69
	v_mul_f32_e32 v96, 0x3fb8aa3b, v84
	v_exp_f32_e32 v84, v95
	v_add_f32_e32 v69, v80, v69
	v_exp_f32_e32 v85, v96
	v_add_f32_e32 v69, v81, v69
	v_add_f32_e32 v69, v82, v69
	v_add_f32_e32 v69, v83, v69
	v_add_f32_e32 v69, v84, v69
	v_add_f32_e32 v69, v85, v69
	v_mov_b32_e32 v86, v69
	s_nop 1
	v_permlane16_swap_b32_e32 v69, v86
	v_add_f32_e32 v69, v69, v86
	v_mov_b32_e32 v86, v69
	s_nop 1
	v_permlane32_swap_b32_e32 v69, v86
	s_and_saveexec_b64 s[18:19], s[12:13]
	v_add_f32_e32 v69, v69, v86
	v_add_u32_e32 v86, s22, v217
	ds_write_b64 v86, v[68:69] offset:61984
	s_or_b64 exec, exec, s[18:19]
	v_cvt_pk_bf16_f32 v137, v72, v73
	ds_read_u16 v68, v221
	ds_read_u16 v72, v221 offset:32
	v_mov_b32_e32 v69, v164
	v_mov_b32_e32 v73, v164
	v_cvt_pk_bf16_f32 v136, v70, v71
	s_waitcnt lgkmcnt(1)
	v_lshlrev_b32_e32 v68, 8, v68
	s_waitcnt lgkmcnt(0)
	v_lshlrev_b32_e32 v72, 8, v72
	v_lshl_add_u64 v[68:69], v[176:177], 0, v[68:69]
	v_lshl_add_u64 v[72:73], v[176:177], 0, v[72:73]
	v_cvt_pk_bf16_f32 v138, v74, v75
	v_cvt_pk_bf16_f32 v139, v76, v77
	v_cvt_pk_bf16_f32 v132, v78, v79
	v_cvt_pk_bf16_f32 v133, v80, v81
	v_cvt_pk_bf16_f32 v134, v82, v83
	v_cvt_pk_bf16_f32 v135, v84, v85
	v_cvt_pk_bf16_f32 v144, v102, v103
	v_cvt_pk_bf16_f32 v145, v104, v105
	v_cvt_pk_bf16_f32 v146, v106, v107
	v_cvt_pk_bf16_f32 v147, v108, v109
	v_cvt_pk_bf16_f32 v140, v110, v111
	v_cvt_pk_bf16_f32 v141, v112, v113
	v_cvt_pk_bf16_f32 v142, v114, v115
	global_load_dwordx4 v[108:111], v[68:69], off
	global_load_dwordx4 v[100:103], v[68:69], off offset:64
	global_load_dwordx4 v[76:79], v[68:69], off offset:128
	s_nop 0
	global_load_dwordx4 v[68:71], v[68:69], off offset:192
	s_nop 0
	global_load_dwordx4 v[112:115], v[72:73], off
	global_load_dwordx4 v[104:107], v[72:73], off offset:64
	global_load_dwordx4 v[80:83], v[72:73], off offset:128
	s_nop 0
	global_load_dwordx4 v[72:75], v[72:73], off offset:192
	ds_read_u16 v84, v221 offset:64
	v_mov_b32_e32 v85, v164
	v_cvt_pk_bf16_f32 v143, v116, v117
	v_mov_b32_e32 v93, v164
	v_add_u32_e32 v148, v216, v168
	s_waitcnt lgkmcnt(0)
	v_lshlrev_b32_e32 v84, 8, v84
	v_lshl_add_u64 v[84:85], v[176:177], 0, v[84:85]
	global_load_dwordx4 v[120:123], v[84:85], off
	global_load_dwordx4 v[116:119], v[84:85], off offset:64
	global_load_dwordx4 v[88:91], v[84:85], off offset:128
	s_nop 0
	global_load_dwordx4 v[84:87], v[84:85], off offset:192
	ds_read_u16 v92, v221 offset:96
	v_add_u32_e32 v222, v213, v214
	s_waitcnt lgkmcnt(0)
	v_lshlrev_b32_e32 v92, 8, v92
	v_lshl_add_u64 v[92:93], v[176:177], 0, v[92:93]
	global_load_dwordx4 v[128:131], v[92:93], off
	global_load_dwordx4 v[124:127], v[92:93], off offset:64
	global_load_dwordx4 v[96:99], v[92:93], off offset:128
	s_nop 0
	global_load_dwordx4 v[92:95], v[92:93], off offset:192
	ds_write_b128 v148, v[24:27] offset:24576
	ds_write_b128 v148, v[28:31] offset:25728
	ds_write_b128 v148, v[36:39] offset:26880
	ds_write_b128 v148, v[40:43] offset:28032
	ds_write_b128 v148, v[44:47] offset:29184
	ds_write_b128 v148, v[52:55] offset:30336
	ds_write_b128 v148, v[56:59] offset:31488
	ds_write_b128 v148, v[60:63] offset:32640
	ds_read_b64_tr_b16 v[26:27], v222 offset:29184
	ds_read_b64_tr_b16 v[24:25], v222 offset:24576
	ds_read_b64_tr_b16 v[28:29], v222 offset:24608
	ds_read_b64_tr_b16 v[30:31], v222 offset:29216
	ds_read_b64_tr_b16 v[36:37], v222 offset:24640
	ds_read_b64_tr_b16 v[38:39], v222 offset:29248
	ds_read_b64_tr_b16 v[40:41], v222 offset:24672
	ds_read_b64_tr_b16 v[42:43], v222 offset:29280
	ds_read_b64_tr_b16 v[44:45], v222 offset:24704
	ds_read_b64_tr_b16 v[46:47], v222 offset:29312
	ds_read_b64_tr_b16 v[52:53], v222 offset:24736
	ds_read_b64_tr_b16 v[54:55], v222 offset:29344
	ds_read_b64_tr_b16 v[56:57], v222 offset:24768
	ds_read_b64_tr_b16 v[58:59], v222 offset:29376
	ds_read_b64_tr_b16 v[60:61], v222 offset:24800
	ds_read_b64_tr_b16 v[62:63], v222 offset:29408
	s_waitcnt lgkmcnt(14)
	v_mfma_f32_16x16x32_bf16 v[24:27], v[24:27], v[144:147], 0
	ds_write_b128 v148, v[4:7] offset:24576
	ds_write_b128 v148, v[8:11] offset:25728
	ds_write_b128 v148, v[12:15] offset:26880
	ds_write_b128 v148, v[16:19] offset:28032
	ds_write_b128 v148, v[20:23] offset:29184
	ds_write_b128 v148, v[32:35] offset:30336
	ds_write_b128 v148, v[48:51] offset:31488
	ds_write_b128 v148, v[64:67] offset:32640
	ds_read_b64_tr_b16 v[6:7], v222 offset:29184
	ds_read_b64_tr_b16 v[4:5], v222 offset:24576
	ds_read_b64_tr_b16 v[8:9], v222 offset:24608
	ds_read_b64_tr_b16 v[10:11], v222 offset:29216
	s_waitcnt lgkmcnt(14)
; DI void dsa_task(const Params& p, int l, int isP, int b, int tq, char* smem, const bool dry) {
;     ...
;             o[j][dt] = mfma16(af, pb[j][0].v, o[j][dt]);
;           }
;         __builtin_amdgcn_wave_barrier();
;       }
;       {
;         *(uint4*)(vst + (0 + g4) * 288 + cl * 16) = vq8;
;         *(uint4*)(vst + (4 + g4) * 288 + cl * 16) = vq9;
;         *(uint4*)(vst + (8 + g4) * 288 + cl * 16) = vq10;
;         *(uint4*)(vst + (12 + g4) * 288 + cl * 16) = vq11;
;         *(uint4*)(vst + (16 + g4) * 288 + cl * 16) = vq12;
;         *(uint4*)(vst + (20 + g4) * 288 + cl * 16) = vq13;
;         *(uint4*)(vst + (24 + g4) * 288 + cl * 16) = vq14;
;         *(uint4*)(vst + (28 + g4) * 288 + cl * 16) = vq15;
;         __builtin_amdgcn_wave_barrier();
; #pragma unroll
;         for (int j = 0; j < 2; j++)
; #pragma unroll
;           for (int dt = 0; dt < 4; dt++) {
;             const s16x4 alo = vtr(vb + (j * 64 + dt * 16) * 2);
;             const s16x4 ahi = vtr(vb + (j * 64 + dt * 16) * 2 + 16 * 288);
;             const bf16x8 af = __builtin_shufflevector(alo, ahi, 0, 1, 2, 3, 4, 5, 6, 7);
;             o[j][dt] = mfma16(af, pb[j][1].v, o[j][dt]);
;           }
;         __builtin_amdgcn_wave_barrier();
;       }
;       vq0 = *(const uint4*)(Vs + (size_t)idxl[qn * 256 + wave * 64 + 0 + g4] * 128 + cl * 8);
;       vq1 = *(const uint4*)(Vs + (size_t)idxl[qn * 256 + wave * 64 + 4 + g4] * 128 + cl * 8);
;       vq2 = *(const uint4*)(Vs + (size_t)idxl[qn * 256 + wave * 64 + 8 + g4] * 128 + cl * 8);
;       vq3 = *(const uint4*)(Vs + (size_t)idxl[qn * 256 + wave * 64 + 12 + g4] * 128 + cl * 8);
;       vq4 = *(const uint4*)(Vs + (size_t)idxl[qn * 256 + wave * 64 + 16 + g4] * 128 + cl * 8);
;       vq5 = *(const uint4*)(Vs + (size_t)idxl[qn * 256 + wave * 64 + 20 + g4] * 128 + cl * 8);
;       vq6 = *(const uint4*)(Vs + (size_t)idxl[qn * 256 + wave * 64 + 24 + g4] * 128 + cl * 8);
;       vq7 = *(const uint4*)(Vs + (size_t)idxl[qn * 256 + wave * 64 + 28 + g4] * 128 + cl * 8);
;       vq8 = *(const uint4*)(Vs + (size_t)idxl[qn * 256 + wave * 64 + 32 + g4] * 128 + cl * 8);
;       vq9 = *(const uint4*)(Vs + (size_t)idxl[qn * 256 + wave * 64 + 36 + g4] * 128 + cl * 8);
;       vq10 = *(const uint4*)(Vs + (size_t)idxl[qn * 256 + wave * 64 + 40 + g4] * 128 + cl * 8);
;       vq11 = *(const uint4*)(Vs + (size_t)idxl[qn * 256 + wave * 64 + 44 + g4] * 128 + cl * 8);
	v_mfma_f32_16x16x32_bf16 v[44:47], v[44:47], v[136:139], 0
	v_mov_b32_e32 v13, v164
	v_mov_b32_e32 v17, v164
	v_mov_b32_e32 v21, v164
	v_mfma_f32_16x16x32_bf16 v[52:55], v[52:55], v[136:139], 0
	v_mov_b32_e32 v33, v164
	v_mov_b32_e32 v49, v164
	v_mov_b32_e32 v65, v164
	v_mfma_f32_16x16x32_bf16 v[56:59], v[56:59], v[136:139], 0
	s_waitcnt lgkmcnt(12)
	v_mfma_f32_16x16x32_bf16 v[60:63], v[60:63], v[136:139], 0
	s_waitcnt lgkmcnt(2)
	v_mfma_f32_16x16x32_bf16 v[136:139], v[4:7], v[140:143], v[24:27]
	ds_read_b64_tr_b16 v[4:5], v222 offset:24640
	ds_read_b64_tr_b16 v[6:7], v222 offset:29248
	v_mfma_f32_16x16x32_bf16 v[36:39], v[36:39], v[144:147], 0
	s_waitcnt lgkmcnt(0)
	v_mfma_f32_16x16x32_bf16 v[148:151], v[4:7], v[140:143], v[36:39]
	ds_read_b64_tr_b16 v[4:5], v222 offset:24672
	ds_read_b64_tr_b16 v[6:7], v222 offset:29280
	v_mfma_f32_16x16x32_bf16 v[28:31], v[28:31], v[144:147], 0
	v_mfma_f32_16x16x32_bf16 v[40:43], v[40:43], v[144:147], 0
	v_mfma_f32_16x16x32_bf16 v[144:147], v[8:11], v[140:143], v[28:31]
	s_waitcnt lgkmcnt(0)
	v_mfma_f32_16x16x32_bf16 v[140:143], v[4:7], v[140:143], v[40:43]
	ds_read_b64_tr_b16 v[4:5], v222 offset:24704
	ds_read_b64_tr_b16 v[6:7], v222 offset:29312
	s_waitcnt lgkmcnt(0)
	v_mfma_f32_16x16x32_bf16 v[152:155], v[4:7], v[132:135], v[44:47]
	ds_read_b64_tr_b16 v[4:5], v222 offset:24736
	ds_read_b64_tr_b16 v[6:7], v222 offset:29344
	s_waitcnt lgkmcnt(0)
	v_mfma_f32_16x16x32_bf16 v[156:159], v[4:7], v[132:135], v[52:55]
	ds_read_b64_tr_b16 v[4:5], v222 offset:24768
	ds_read_b64_tr_b16 v[6:7], v222 offset:29376
	s_waitcnt lgkmcnt(0)
	v_mfma_f32_16x16x32_bf16 v[160:163], v[4:7], v[132:135], v[56:59]
	ds_read_b64_tr_b16 v[4:5], v222 offset:24800
	ds_read_b64_tr_b16 v[6:7], v222 offset:29408
	s_waitcnt lgkmcnt(0)
	v_mfma_f32_16x16x32_bf16 v[132:135], v[4:7], v[132:135], v[60:63]
	ds_read_u16 v4, v220
	ds_read_u16 v6, v220 offset:8
	ds_read_u16 v7, v220 offset:16
	ds_read_u16 v8, v220 offset:24
	ds_read_u16 v9, v220 offset:32
	ds_read_u16 v10, v220 offset:40
	ds_read_u16 v11, v220 offset:48
	ds_read_u16 v12, v220 offset:56
	s_waitcnt lgkmcnt(7)
	v_lshlrev_b32_e32 v4, 8, v4
	v_mov_b32_e32 v5, v164
	v_lshl_add_u64 v[4:5], v[178:179], 0, v[4:5]
	global_load_dwordx4 v[24:27], v[4:5], off
	s_waitcnt lgkmcnt(6)
	v_lshlrev_b32_e32 v4, 8, v6
	v_mov_b32_e32 v5, v164
	v_lshl_add_u64 v[4:5], v[178:179], 0, v[4:5]
	global_load_dwordx4 v[28:31], v[4:5], off
	s_waitcnt lgkmcnt(5)
	v_lshlrev_b32_e32 v4, 8, v7
	v_mov_b32_e32 v5, v164
	v_lshl_add_u64 v[4:5], v[178:179], 0, v[4:5]
	global_load_dwordx4 v[36:39], v[4:5], off
	s_waitcnt lgkmcnt(4)
	v_lshlrev_b32_e32 v4, 8, v8
	v_mov_b32_e32 v5, v164
	v_lshl_add_u64 v[4:5], v[178:179], 0, v[4:5]
	global_load_dwordx4 v[40:43], v[4:5], off
	s_waitcnt lgkmcnt(3)
	v_lshlrev_b32_e32 v4, 8, v9
	v_mov_b32_e32 v5, v164
	v_lshl_add_u64 v[4:5], v[178:179], 0, v[4:5]
	global_load_dwordx4 v[44:47], v[4:5], off
	s_waitcnt lgkmcnt(2)
	v_lshlrev_b32_e32 v4, 8, v10
	v_mov_b32_e32 v5, v164
	v_lshl_add_u64 v[4:5], v[178:179], 0, v[4:5]
	global_load_dwordx4 v[52:55], v[4:5], off
	s_waitcnt lgkmcnt(1)
	v_lshlrev_b32_e32 v4, 8, v11
	v_mov_b32_e32 v5, v164
	v_lshl_add_u64 v[4:5], v[178:179], 0, v[4:5]
	global_load_dwordx4 v[56:59], v[4:5], off
	s_waitcnt lgkmcnt(0)
	v_lshlrev_b32_e32 v4, 8, v12
	v_mov_b32_e32 v5, v164
	v_lshl_add_u64 v[4:5], v[178:179], 0, v[4:5]
	global_load_dwordx4 v[60:63], v[4:5], off
	ds_read_u16 v4, v220 offset:64
	ds_read_u16 v8, v220 offset:72
	ds_read_u16 v12, v220 offset:80
	ds_read_u16 v16, v220 offset:88
	ds_read_u16 v20, v220 offset:96
	ds_read_u16 v32, v220 offset:104
	ds_read_u16 v48, v220 offset:112
	ds_read_u16 v64, v220 offset:120
	s_waitcnt lgkmcnt(7)
	v_lshlrev_b32_e32 v4, 8, v4
	v_mov_b32_e32 v5, v164
	s_waitcnt lgkmcnt(6)
	v_lshlrev_b32_e32 v8, 8, v8
	v_mov_b32_e32 v9, v164
	s_waitcnt lgkmcnt(5)
	v_lshlrev_b32_e32 v12, 8, v12
	s_waitcnt lgkmcnt(4)
	v_lshlrev_b32_e32 v16, 8, v16
	s_waitcnt lgkmcnt(3)
	v_lshlrev_b32_e32 v20, 8, v20
	s_waitcnt lgkmcnt(2)
	v_lshlrev_b32_e32 v32, 8, v32
	s_waitcnt lgkmcnt(1)
	v_lshlrev_b32_e32 v48, 8, v48
	s_waitcnt lgkmcnt(0)
	v_lshlrev_b32_e32 v64, 8, v64
	v_lshl_add_u64 v[4:5], v[178:179], 0, v[4:5]
	v_lshl_add_u64 v[8:9], v[178:179], 0, v[8:9]
	v_lshl_add_u64 v[12:13], v[178:179], 0, v[12:13]
	v_lshl_add_u64 v[16:17], v[178:179], 0, v[16:17]
	v_lshl_add_u64 v[20:21], v[178:179], 0, v[20:21]
	v_lshl_add_u64 v[32:33], v[178:179], 0, v[32:33]
	v_lshl_add_u64 v[48:49], v[178:179], 0, v[48:49]
	v_lshl_add_u64 v[64:65], v[178:179], 0, v[64:65]
	global_load_dwordx4 v[4:7], v[4:5], off
	s_nop 0
	global_load_dwordx4 v[8:11], v[8:9], off
	s_nop 0
	global_load_dwordx4 v[12:15], v[12:13], off
	s_nop 0
	global_load_dwordx4 v[16:19], v[16:17], off
	s_nop 0
	global_load_dwordx4 v[20:23], v[20:21], off
	s_nop 0
	global_load_dwordx4 v[32:35], v[32:33], off
	s_nop 0
	global_load_dwordx4 v[48:51], v[48:49], off
	s_nop 0
	global_load_dwordx4 v[64:67], v[64:65], off
	s_and_saveexec_b64 s[18:19], vcc
	s_cbranch_execz .LBB0_1650
	v_lshl_add_u32 v222, v211, 2, s21
	v_add3_u32 v222, v222, v175, v212
	ds_write_b128 v222, v[136:139]
	ds_write_b128 v222, v[144:147] offset:64
	ds_write_b128 v222, v[148:151] offset:128
	ds_write_b128 v222, v[140:143] offset:192
	ds_write_b128 v222, v[152:155] offset:1024
	ds_write_b128 v222, v[156:159] offset:1088
	ds_write_b128 v222, v[160:163] offset:1152
	ds_write_b128 v222, v[132:135] offset:1216
	s_branch .LBB0_1650

; DI f32x4 mfma16(bf16x8 a, bf16x8 b, f32x4 c) { return __builtin_amdgcn_mfma_f32_16x16x32_bf16(a, b, c, 0, 0, 0); }
; DI void dsa_task(const Params& p, int l, int isP, int b, int tq, char* smem, const bool dry) {
;     ...
; #pragma unroll
;       for (int j = 0; j < 2; j++) {
;         const bf16_t* qp = p.qa + (size_t)tok * 512 + (j * 4 + (cl & 3)) * 64 + g4 * 8;
;         const bf16x8 bq0 = *(const bf16x8*)qp;
;         const bf16x8 bq1 = *(const bf16x8*)(qp + 32);
;         f32x4 lg[4];
; #pragma unroll
;         for (int tt = 0; tt < 4; tt++) {
;           f32x4 a = (f32x4){0.f, 0.f, 0.f, 0.f};
;           a = mfma16(kf[j][tt][0], bq0, a);
;           a = mfma16(kf[j][tt][1], bq1, a);
;           lg[tt] = a;
;         }
;         float m = -1e30f;
; #pragma unroll
;         for (int tt = 0; tt < 4; tt++)
; #pragma unroll
;           for (int r = 0; r < 4; r++) m = fmaxf(m, lg[tt][r]);
;         m = red4_max(m);
;         float sum = 0.f;
; #pragma unroll
;         for (int tt = 0; tt < 4; tt++)
; #pragma unroll
;           for (int r = 0; r < 4; r++) {
;             const float e = __expf(lg[tt][r] - m);
;             lg[tt][r] = e;
;             sum += e;
;           }
;         sum = red4_sum(sum);
; #pragma unroll
;         for (int sI = 0; sI < 2; sI++) {
;           pb[j][sI].u[0] = pack2(lg[2 * sI][0], lg[2 * sI][1]);
;           pb[j][sI].u[1] = pack2(lg[2 * sI][2], lg[2 * sI][3]);
;           pb[j][sI].u[2] = pack2(lg[2 * sI + 1][0], lg[2 * sI + 1][1]);
;           pb[j][sI].u[3] = pack2(lg[2 * sI + 1][2], lg[2 * sI + 1][3]);
;         }
;         if (cl < 4 && g4 == 0) {
;           mlb[(wave * 8 + j * 4 + cl) * 2] = m;
;           mlb[(wave * 8 + j * 4 + cl) * 2 + 1] = sum;
;         }
.LBB0_1667:
	s_or_saveexec_b64 s[6:7], s[6:7]
	v_mov_b64_e32 v[132:133], s[16:17]
	s_xor_b64 exec, exec, s[6:7]
	s_cbranch_execz .LBB0_1675
	s_mov_b32 s15, s45
	s_lshl_b64 s[8:9], s[14:15], 10
	s_add_u32 s14, s10, s8
	s_addc_u32 s15, s11, s9
	v_lshl_add_u64 v[132:133], v[172:173], 1, s[14:15]
	v_lshlrev_b32_e32 v134, 1, v174
	v_mov_b32_e32 v135, v164
	v_lshl_add_u64 v[132:133], v[132:133], 0, v[134:135]
	global_load_dwordx4 v[134:137], v[132:133], off
	global_load_dwordx4 v[224:227], v[132:133], off offset:64
	global_load_dwordx4 v[228:231], v[132:133], off offset:512
	global_load_dwordx4 v[232:235], v[132:133], off offset:576
	s_waitcnt vmcnt(0)
	v_mfma_f32_16x16x32_bf16 v[108:111], v[108:111], v[134:137], 0
	v_mfma_f32_16x16x32_bf16 v[112:115], v[112:115], v[134:137], 0
	v_mfma_f32_16x16x32_bf16 v[120:123], v[120:123], v[134:137], 0
	v_mfma_f32_16x16x32_bf16 v[128:131], v[128:131], v[134:137], 0
	v_mfma_f32_16x16x32_bf16 v[108:111], v[100:103], v[224:227], v[108:111]
	s_nop 7
	v_max3_f32 v100, v108, s77, v109
	v_mfma_f32_16x16x32_bf16 v[102:105], v[104:107], v[224:227], v[112:115]
	v_max3_f32 v100, v100, v110, v111
	v_mfma_f32_16x16x32_bf16 v[112:115], v[116:119], v[224:227], v[120:123]
	v_mfma_f32_16x16x32_bf16 v[116:119], v[124:127], v[224:227], v[128:131]
	s_nop 4
	v_max3_f32 v100, v100, v102, v103
	v_max3_f32 v100, v100, v104, v105
	v_max3_f32 v100, v100, v112, v113
	v_max3_f32 v100, v100, v114, v115
	v_max3_f32 v100, v100, v116, v117
	v_max3_f32 v100, v100, v118, v119
	v_mov_b32_e32 v101, v100
	s_nop 1
	v_permlane16_swap_b32_e32 v100, v101
	v_max_f32_e32 v101, v101, v101
	v_max_f32_e32 v100, v100, v100
	v_max_f32_e32 v100, v100, v101
	v_mov_b32_e32 v101, v100
	s_nop 1
	v_permlane32_swap_b32_e32 v100, v101
	v_max_f32_e32 v101, v101, v101
	v_max_f32_e32 v100, v100, v100
	v_max_f32_e32 v100, v100, v101
	v_sub_f32_e32 v101, v108, v100
	v_sub_f32_e32 v106, v109, v100
	v_sub_f32_e32 v109, v112, v100
	v_sub_f32_e32 v112, v115, v100
	v_mul_f32_e32 v101, 0x3fb8aa3b, v101
	v_sub_f32_e32 v107, v110, v100
	v_sub_f32_e32 v110, v113, v100
	v_sub_f32_e32 v113, v116, v100
	v_mul_f32_e32 v106, 0x3fb8aa3b, v106
	v_mul_f32_e32 v120, 0x3fb8aa3b, v112
	v_exp_f32_e32 v112, v101
	v_sub_f32_e32 v108, v111, v100
	v_sub_f32_e32 v111, v114, v100
	v_sub_f32_e32 v114, v117, v100
	v_mul_f32_e32 v107, 0x3fb8aa3b, v107
	v_mul_f32_e32 v121, 0x3fb8aa3b, v113
	v_exp_f32_e32 v113, v106
	v_sub_f32_e32 v102, v102, v100
	v_sub_f32_e32 v115, v118, v100
	v_mul_f32_e32 v108, 0x3fb8aa3b, v108
	v_mul_f32_e32 v122, 0x3fb8aa3b, v114
	v_exp_f32_e32 v114, v107
	v_sub_f32_e32 v103, v103, v100
	v_sub_f32_e32 v116, v119, v100
	v_mul_f32_e32 v102, 0x3fb8aa3b, v102
	v_mul_f32_e32 v123, 0x3fb8aa3b, v115
	v_exp_f32_e32 v115, v108
	v_sub_f32_e32 v104, v104, v100
	v_mul_f32_e32 v103, 0x3fb8aa3b, v103
	v_mul_f32_e32 v124, 0x3fb8aa3b, v116
	v_exp_f32_e32 v116, v102
	v_add_f32_e32 v101, 0, v112
	v_sub_f32_e32 v105, v105, v100
	v_mul_f32_e32 v104, 0x3fb8aa3b, v104
	v_exp_f32_e32 v117, v103
	v_add_f32_e32 v101, v113, v101
	v_mul_f32_e32 v105, 0x3fb8aa3b, v105
	v_mul_f32_e32 v118, 0x3fb8aa3b, v110
	v_exp_f32_e32 v110, v104
	v_add_f32_e32 v101, v114, v101
	v_mul_f32_e32 v109, 0x3fb8aa3b, v109
	v_mul_f32_e32 v119, 0x3fb8aa3b, v111
	v_exp_f32_e32 v111, v105
	v_add_f32_e32 v101, v115, v101
	v_exp_f32_e32 v104, v109
	v_add_f32_e32 v101, v116, v101
	v_exp_f32_e32 v105, v118
	v_add_f32_e32 v101, v117, v101
	v_exp_f32_e32 v106, v119
	v_add_f32_e32 v101, v110, v101
	v_exp_f32_e32 v107, v120
	v_add_f32_e32 v101, v111, v101
	v_exp_f32_e32 v108, v121
	v_add_f32_e32 v101, v104, v101
	v_exp_f32_e32 v109, v122
	v_add_f32_e32 v101, v105, v101
	v_exp_f32_e32 v102, v123
	v_add_f32_e32 v101, v106, v101
	v_exp_f32_e32 v103, v124
	v_add_f32_e32 v101, v107, v101
	v_add_f32_e32 v101, v108, v101
	v_add_f32_e32 v101, v109, v101
	v_add_f32_e32 v101, v102, v101
	v_add_f32_e32 v101, v103, v101
	v_mov_b32_e32 v118, v101
	s_nop 1
	v_permlane16_swap_b32_e32 v101, v118
	v_add_f32_e32 v101, v101, v118
	v_mov_b32_e32 v118, v101
	s_nop 1
	v_permlane32_swap_b32_e32 v101, v118
	s_and_saveexec_b64 s[14:15], s[12:13]
	v_add_f32_e32 v101, v101, v118
	ds_write_b64 v217, v[100:101] offset:62208
	s_or_b64 exec, exec, s[14:15]
	v_mfma_f32_16x16x32_bf16 v[76:79], v[76:79], v[228:231], 0
	v_mfma_f32_16x16x32_bf16 v[80:83], v[80:83], v[228:231], 0
	v_mfma_f32_16x16x32_bf16 v[88:91], v[88:91], v[228:231], 0
	v_mfma_f32_16x16x32_bf16 v[96:99], v[96:99], v[228:231], 0
	v_mfma_f32_16x16x32_bf16 v[76:79], v[68:71], v[232:235], v[76:79]
	s_nop 7
	v_max3_f32 v68, v76, s77, v77
	v_mfma_f32_16x16x32_bf16 v[70:73], v[72:75], v[232:235], v[80:83]
	v_max3_f32 v68, v68, v78, v79
	v_mfma_f32_16x16x32_bf16 v[80:83], v[84:87], v[232:235], v[88:91]
	v_mfma_f32_16x16x32_bf16 v[84:87], v[92:95], v[232:235], v[96:99]
	s_nop 4
	v_max3_f32 v68, v68, v70, v71
	v_max3_f32 v68, v68, v72, v73
	v_max3_f32 v68, v68, v80, v81
	v_max3_f32 v68, v68, v82, v83
	v_max3_f32 v68, v68, v84, v85
	v_max3_f32 v68, v68, v86, v87
	v_mov_b32_e32 v69, v68
	s_nop 1
	v_permlane16_swap_b32_e32 v68, v69
	v_max_f32_e32 v69, v69, v69
	v_max_f32_e32 v68, v68, v68
	v_max_f32_e32 v68, v68, v69
	v_mov_b32_e32 v69, v68
	s_nop 1
	v_permlane32_swap_b32_e32 v68, v69
	v_max_f32_e32 v69, v69, v69
	v_max_f32_e32 v68, v68, v68
	v_max_f32_e32 v68, v68, v69
	v_sub_f32_e32 v69, v76, v68
	v_sub_f32_e32 v74, v77, v68
	v_sub_f32_e32 v75, v78, v68
	v_sub_f32_e32 v78, v81, v68
	v_mul_f32_e32 v69, 0x3fb8aa3b, v69
	v_sub_f32_e32 v77, v80, v68
	v_sub_f32_e32 v80, v83, v68
	v_sub_f32_e32 v83, v86, v68
	v_mul_f32_e32 v74, 0x3fb8aa3b, v74
	v_mul_f32_e32 v86, 0x3fb8aa3b, v78
	v_exp_f32_e32 v78, v69
; DI void dsa_task(const Params& p, int l, int isP, int b, int tq, char* smem, const bool dry) {
;     ...
;             const float e = __expf(lg[tt][r] - m);
;             lg[tt][r] = e;
;             sum += e;
;           }
;         sum = red4_sum(sum);
; #pragma unroll
;         for (int sI = 0; sI < 2; sI++) {
;           pb[j][sI].u[0] = pack2(lg[2 * sI][0], lg[2 * sI][1]);
;           pb[j][sI].u[1] = pack2(lg[2 * sI][2], lg[2 * sI][3]);
;           pb[j][sI].u[2] = pack2(lg[2 * sI + 1][0], lg[2 * sI + 1][1]);
;           pb[j][sI].u[3] = pack2(lg[2 * sI + 1][2], lg[2 * sI + 1][3]);
;         }
;         if (cl < 4 && g4 == 0) {
;           mlb[(wave * 8 + j * 4 + cl) * 2] = m;
;           mlb[(wave * 8 + j * 4 + cl) * 2 + 1] = sum;
;         }
;       }
; #pragma unroll
;       for (int tt = 0; tt < 4; tt++) {
;         const int pos = idxl[qn * 256 + wave * 64 + tt * 16 + cl];
; #pragma unroll
;         for (int j = 0; j < 2; j++) {
;           const bf16_t* kr = Ks + (size_t)pos * 128 + j * 64 + g4 * 8;
;           kf[j][tt][0] = *(const bf16x8*)kr;
;           kf[j][tt][1] = *(const bf16x8*)(kr + 32);
;         }
;       }
;       f32x4 o[2][4];
; #pragma unroll
;       for (int j = 0; j < 2; j++)
; #pragma unroll
;         for (int dt = 0; dt < 4; dt++) o[j][dt] = (f32x4){0.f, 0.f, 0.f, 0.f};
;       const lds_cptr vb = (lds_cptr)(vst + (g4 * 4 + (cl >> 2)) * 288 + (cl & 3) * 8);
;       {
;         *(uint4*)(vst + (0 + g4) * 288 + cl * 16) = vq0;
;         *(uint4*)(vst + (4 + g4) * 288 + cl * 16) = vq1;
;         *(uint4*)(vst + (8 + g4) * 288 + cl * 16) = vq2;
;         *(uint4*)(vst + (12 + g4) * 288 + cl * 16) = vq3;
;         *(uint4*)(vst + (16 + g4) * 288 + cl * 16) = vq4;
;         *(uint4*)(vst + (20 + g4) * 288 + cl * 16) = vq5;
;         *(uint4*)(vst + (24 + g4) * 288 + cl * 16) = vq6;
;         *(uint4*)(vst + (28 + g4) * 288 + cl * 16) = vq7;
;         __builtin_amdgcn_wave_barrier();
; #pragma unroll
;         for (int j = 0; j < 2; j++)
; #pragma unroll
;           for (int dt = 0; dt < 4; dt++) {
;             const s16x4 alo = vtr(vb + (j * 64 + dt * 16) * 2);
;             const s16x4 ahi = vtr(vb + (j * 64 + dt * 16) * 2 + 16 * 288);
;             const bf16x8 af = __builtin_shufflevector(alo, ahi, 0, 1, 2, 3, 4, 5, 6, 7);
;             o[j][dt] = mfma16(af, pb[j][0].v, o[j][dt]);
;           }
	v_sub_f32_e32 v76, v79, v68
	v_sub_f32_e32 v81, v84, v68
	v_mul_f32_e32 v75, 0x3fb8aa3b, v75
	v_mul_f32_e32 v88, 0x3fb8aa3b, v80
	v_exp_f32_e32 v80, v74
	v_sub_f32_e32 v70, v70, v68
	v_sub_f32_e32 v84, v87, v68
	v_mul_f32_e32 v76, 0x3fb8aa3b, v76
	v_mul_f32_e32 v89, 0x3fb8aa3b, v81
	v_exp_f32_e32 v81, v75
	v_sub_f32_e32 v71, v71, v68
	v_sub_f32_e32 v79, v82, v68
	v_mul_f32_e32 v70, 0x3fb8aa3b, v70
	v_mul_f32_e32 v92, 0x3fb8aa3b, v84
	v_exp_f32_e32 v84, v76
	v_sub_f32_e32 v72, v72, v68
	v_sub_f32_e32 v82, v85, v68
	v_mul_f32_e32 v71, 0x3fb8aa3b, v71
	v_mul_f32_e32 v87, 0x3fb8aa3b, v79
	v_exp_f32_e32 v79, v70
	v_add_f32_e32 v69, 0, v78
	v_sub_f32_e32 v73, v73, v68
	v_mul_f32_e32 v72, 0x3fb8aa3b, v72
	v_mul_f32_e32 v90, 0x3fb8aa3b, v82
	v_exp_f32_e32 v82, v71
	v_add_f32_e32 v69, v80, v69
	v_mul_f32_e32 v73, 0x3fb8aa3b, v73
	v_mul_f32_e32 v91, 0x3fb8aa3b, v83
	v_exp_f32_e32 v83, v72
	v_add_f32_e32 v69, v81, v69
	v_mul_f32_e32 v77, 0x3fb8aa3b, v77
	v_exp_f32_e32 v85, v73
	v_add_f32_e32 v69, v84, v69
	v_exp_f32_e32 v70, v77
	v_add_f32_e32 v69, v79, v69
	v_exp_f32_e32 v72, v86
	v_add_f32_e32 v69, v82, v69
	v_exp_f32_e32 v73, v87
	v_add_f32_e32 v69, v83, v69
	v_exp_f32_e32 v76, v88
	v_add_f32_e32 v69, v85, v69
	v_exp_f32_e32 v71, v89
	v_add_f32_e32 v69, v70, v69
	v_exp_f32_e32 v74, v90
	v_add_f32_e32 v69, v72, v69
	v_exp_f32_e32 v75, v91
	v_add_f32_e32 v69, v73, v69
	v_exp_f32_e32 v77, v92
	v_add_f32_e32 v69, v76, v69
	v_add_f32_e32 v69, v71, v69
	v_add_f32_e32 v69, v74, v69
	v_add_f32_e32 v69, v75, v69
	v_add_f32_e32 v69, v77, v69
	v_mov_b32_e32 v86, v69
	s_nop 1
	v_permlane16_swap_b32_e32 v69, v86
	v_add_f32_e32 v69, v69, v86
	v_mov_b32_e32 v86, v69
	s_nop 1
	v_permlane32_swap_b32_e32 v69, v86
	s_and_saveexec_b64 s[14:15], s[12:13]
	v_add_f32_e32 v69, v69, v86
	ds_write_b64 v217, v[68:69] offset:62240
	s_or_b64 exec, exec, s[14:15]
	v_add_u32_e32 v68, v216, v168
	v_add_u32_e32 v69, v213, v214
	ds_write_b128 v68, v[24:27] offset:24576
	ds_write_b128 v68, v[28:31] offset:25728
	ds_write_b128 v68, v[36:39] offset:26880
	ds_write_b128 v68, v[40:43] offset:28032
	ds_write_b128 v68, v[44:47] offset:29184
	ds_write_b128 v68, v[52:55] offset:30336
	ds_write_b128 v68, v[56:59] offset:31488
	ds_write_b128 v68, v[60:63] offset:32640
	ds_read_b64_tr_b16 v[26:27], v69 offset:29184
	ds_read_b64_tr_b16 v[24:25], v69 offset:24576
	ds_read_b64_tr_b16 v[38:39], v69 offset:29216
	ds_read_b64_tr_b16 v[36:37], v69 offset:24608
	ds_read_b64_tr_b16 v[40:41], v69 offset:24640
	ds_read_b64_tr_b16 v[44:45], v69 offset:24672
	ds_read_b64_tr_b16 v[42:43], v69 offset:29248
	ds_read_b64_tr_b16 v[46:47], v69 offset:29280
	v_cvt_pk_bf16_f32 v28, v112, v113
	v_cvt_pk_bf16_f32 v29, v114, v115
	v_cvt_pk_bf16_f32 v30, v116, v117
	v_cvt_pk_bf16_f32 v31, v110, v111
	ds_read_b64_tr_b16 v[52:53], v69 offset:24704
	ds_read_b64_tr_b16 v[54:55], v69 offset:29312
	s_waitcnt lgkmcnt(8)
	v_mfma_f32_16x16x32_bf16 v[24:27], v[24:27], v[28:31], 0
	v_cvt_pk_bf16_f32 v56, v78, v80
	v_cvt_pk_bf16_f32 v57, v81, v84
	v_cvt_pk_bf16_f32 v58, v79, v82
	s_waitcnt lgkmcnt(6)
	v_mfma_f32_16x16x32_bf16 v[36:39], v[36:39], v[28:31], 0
	v_cvt_pk_bf16_f32 v59, v83, v85
	s_waitcnt lgkmcnt(3)
	v_mfma_f32_16x16x32_bf16 v[40:43], v[40:43], v[28:31], 0
	s_waitcnt lgkmcnt(2)
	v_mfma_f32_16x16x32_bf16 v[28:31], v[44:47], v[28:31], 0
	ds_read_b64_tr_b16 v[46:47], v69 offset:29344
	ds_read_b64_tr_b16 v[44:45], v69 offset:24736
	ds_read_b64_tr_b16 v[60:61], v69 offset:24768
	ds_read_b64_tr_b16 v[78:79], v69 offset:24800
	ds_read_b64_tr_b16 v[62:63], v69 offset:29376
	ds_read_b64_tr_b16 v[80:81], v69 offset:29408
	ds_write_b128 v68, v[4:7] offset:24576
	ds_write_b128 v68, v[8:11] offset:25728
	ds_write_b128 v68, v[12:15] offset:26880
	ds_write_b128 v68, v[16:19] offset:28032
	ds_write_b128 v68, v[20:23] offset:29184
	ds_write_b128 v68, v[32:35] offset:30336
	ds_write_b128 v68, v[48:51] offset:31488
	ds_write_b128 v68, v[64:67] offset:32640
	ds_read_b64_tr_b16 v[6:7], v69 offset:29184
	ds_read_b64_tr_b16 v[4:5], v69 offset:24576
	ds_read_b64_tr_b16 v[10:11], v69 offset:29216
	ds_read_b64_tr_b16 v[8:9], v69 offset:24608
	ds_read_b64_tr_b16 v[12:13], v69 offset:24640
	ds_read_b64_tr_b16 v[20:21], v69 offset:24672
	ds_read_b64_tr_b16 v[14:15], v69 offset:29248
	ds_read_b64_tr_b16 v[22:23], v69 offset:29280
	v_cvt_pk_bf16_f32 v16, v104, v105
	v_cvt_pk_bf16_f32 v17, v106, v107
	v_cvt_pk_bf16_f32 v18, v108, v109
	v_cvt_pk_bf16_f32 v19, v102, v103
	s_waitcnt lgkmcnt(14)
	v_mfma_f32_16x16x32_bf16 v[52:55], v[52:55], v[56:59], 0
	s_waitcnt lgkmcnt(6)
	v_mfma_f32_16x16x32_bf16 v[4:7], v[4:7], v[16:19], v[24:27]
	s_nop 2
	ds_read_b64_tr_b16 v[24:25], v69 offset:24704
	ds_read_b64_tr_b16 v[26:27], v69 offset:29312
	s_waitcnt lgkmcnt(6)
	v_mfma_f32_16x16x32_bf16 v[8:11], v[8:11], v[16:19], v[36:39]
	s_waitcnt lgkmcnt(3)
	v_mfma_f32_16x16x32_bf16 v[12:15], v[12:15], v[16:19], v[40:43]
	s_nop 0
	v_cvt_pk_bf16_f32 v36, v70, v72
	v_cvt_pk_bf16_f32 v37, v73, v76
	v_cvt_pk_bf16_f32 v38, v71, v74
	s_waitcnt lgkmcnt(2)
	v_mfma_f32_16x16x32_bf16 v[16:19], v[20:23], v[16:19], v[28:31]
	s_nop 2
	ds_read_b64_tr_b16 v[30:31], v69 offset:29344
	ds_read_b64_tr_b16 v[28:29], v69 offset:24736
	ds_read_b64_tr_b16 v[40:41], v69 offset:24768
	ds_read_b64_tr_b16 v[48:49], v69 offset:24800
	ds_read_b64_tr_b16 v[42:43], v69 offset:29376
	ds_read_b64_tr_b16 v[50:51], v69 offset:29408
	v_cvt_pk_bf16_f32 v39, v75, v77
	v_mfma_f32_16x16x32_bf16 v[44:47], v[44:47], v[56:59], 0
	v_mfma_f32_16x16x32_bf16 v[60:63], v[60:63], v[56:59], 0
	v_mfma_f32_16x16x32_bf16 v[32:35], v[78:81], v[56:59], 0
	s_waitcnt lgkmcnt(6)
	v_mfma_f32_16x16x32_bf16 v[20:23], v[24:27], v[36:39], v[52:55]
	s_waitcnt lgkmcnt(4)
	v_mfma_f32_16x16x32_bf16 v[24:27], v[28:31], v[36:39], v[44:47]
	s_waitcnt lgkmcnt(1)
	v_mfma_f32_16x16x32_bf16 v[28:31], v[40:43], v[36:39], v[60:63]
	s_waitcnt lgkmcnt(0)
	v_mfma_f32_16x16x32_bf16 v[32:35], v[48:51], v[36:39], v[32:35]
	s_and_saveexec_b64 s[12:13], vcc
	s_cbranch_execz .LBB0_1674
	v_lshlrev_b32_e32 v36, 2, v211
	v_add3_u32 v36, v36, v175, v212
	ds_write_b128 v36, v[4:7] offset:8192
	ds_write_b128 v36, v[8:11] offset:8256
	ds_write_b128 v36, v[12:15] offset:8320
	ds_write_b128 v36, v[16:19] offset:8384
	ds_write_b128 v36, v[20:23] offset:9216
	ds_write_b128 v36, v[24:27] offset:9280
	ds_write_b128 v36, v[28:31] offset:9344
	ds_write_b128 v36, v[32:35] offset:9408
